# GU epilogue: cost-weighted VALU spacing - interleave exp/rcp with independent muls (sec 7.5), exp chain in temps v222-229
# speedup vs baseline: 1.0006x; 1.0006x over previous
.LBB0_788:
	s_waitcnt lgkmcnt(0)
	v_mul_f32_e32 v246, 0xbfb8aa3b, v16
	v_mul_f32_e32 v247, v16, v16
	v_rcp_f32_e32 v247, v247
	v_mul_f32_e32 v222, v246, v12
	v_mul_f32_e32 v223, v246, v13
	v_mul_f32_e32 v224, v246, v14
	v_mul_f32_e32 v225, v246, v15
	v_mul_f32_e32 v226, v246, v4
	v_mul_f32_e32 v227, v246, v5
	v_mul_f32_e32 v228, v246, v6
	v_mul_f32_e32 v229, v246, v7
	v_exp_f32_e32 v222, v222
	v_mul_f32_e32 v8, v8, v12
	v_exp_f32_e32 v223, v223
	v_mul_f32_e32 v9, v9, v13
	v_exp_f32_e32 v224, v224
	v_mul_f32_e32 v10, v10, v14
	v_exp_f32_e32 v225, v225
	v_mul_f32_e32 v11, v11, v15
	v_exp_f32_e32 v226, v226
	v_mul_f32_e32 v0, v0, v4
	v_exp_f32_e32 v227, v227
	v_mul_f32_e32 v1, v1, v5
	v_exp_f32_e32 v228, v228
	v_mul_f32_e32 v2, v2, v6
	v_exp_f32_e32 v229, v229
	v_mul_f32_e32 v3, v3, v7
	v_fma_f32 v12, v222, v247, v247
	v_fma_f32 v13, v223, v247, v247
	v_fma_f32 v14, v224, v247, v247
	v_fma_f32 v15, v225, v247, v247
	v_fma_f32 v4, v226, v247, v247
	v_fma_f32 v5, v227, v247, v247
	v_fma_f32 v6, v228, v247, v247
	v_fma_f32 v7, v229, v247, v247
	v_rcp_f32_e32 v12, v12
	v_rcp_f32_e32 v13, v13
	v_mul_f32_e32 v8, v8, v12
	v_rcp_f32_e32 v14, v14
	v_mul_f32_e32 v9, v9, v13
	v_rcp_f32_e32 v15, v15
	v_mul_f32_e32 v10, v10, v14
	v_rcp_f32_e32 v4, v4
	v_mul_f32_e32 v11, v11, v15
	v_rcp_f32_e32 v5, v5
	v_mul_f32_e32 v0, v0, v4
	v_rcp_f32_e32 v6, v6
	v_mul_f32_e32 v1, v1, v5
	v_rcp_f32_e32 v7, v7
	v_mul_f32_e32 v2, v2, v6
	v_mul_f32_e32 v3, v3, v7
	v_cvt_pk_bf16_f32 v12, v8, v9
	v_cvt_pk_bf16_f32 v13, v10, v11
	v_cvt_pk_bf16_f32 v14, v0, v1
	v_cvt_pk_bf16_f32 v15, v2, v3
	s_and_b64 vcc, exec, s[6:7]
	s_mov_b32 s8, s18
	s_mov_b32 s28, s20
	s_mov_b64 s[62:63], s[24:25]
	s_mov_b64 s[58:59], s[22:23]
	v_add_u32_e32 v4, v17, v139
	v_mov_b32_e32 v5, 0x16000
	v_lshl_add_u32 v4, v4, 1, v5
	buffer_store_dwordx4 v[12:15], v4, s[36:39], 0 offen sc1
	s_cbranch_vccnz .LBB0_825

.LBB0_797:
	s_waitcnt lgkmcnt(0)
	v_mul_f32_e32 v246, 0xbfb8aa3b, v140
	v_mul_f32_e32 v247, v140, v140
	v_rcp_f32_e32 v247, v247
	v_mul_f32_e32 v222, v246, v124
	v_mul_f32_e32 v223, v246, v125
	v_mul_f32_e32 v224, v246, v126
	v_mul_f32_e32 v225, v246, v127
	v_mul_f32_e32 v226, v246, v116
	v_mul_f32_e32 v227, v246, v117
	v_mul_f32_e32 v228, v246, v118
	v_mul_f32_e32 v229, v246, v119
	v_exp_f32_e32 v222, v222
	v_mul_f32_e32 v120, v120, v124
	v_exp_f32_e32 v223, v223
	v_mul_f32_e32 v121, v121, v125
	v_exp_f32_e32 v224, v224
	v_mul_f32_e32 v122, v122, v126
	v_exp_f32_e32 v225, v225
	v_mul_f32_e32 v123, v123, v127
	v_exp_f32_e32 v226, v226
	v_mul_f32_e32 v112, v112, v116
	v_exp_f32_e32 v227, v227
	v_mul_f32_e32 v113, v113, v117
	v_exp_f32_e32 v228, v228
	v_mul_f32_e32 v114, v114, v118
	v_exp_f32_e32 v229, v229
	v_mul_f32_e32 v115, v115, v119
	v_fma_f32 v124, v222, v247, v247
	v_fma_f32 v125, v223, v247, v247
	v_fma_f32 v126, v224, v247, v247
	v_fma_f32 v127, v225, v247, v247
	v_fma_f32 v116, v226, v247, v247
	v_fma_f32 v117, v227, v247, v247
	v_fma_f32 v118, v228, v247, v247
	v_fma_f32 v119, v229, v247, v247
	v_rcp_f32_e32 v124, v124
	v_rcp_f32_e32 v125, v125
	v_mul_f32_e32 v120, v120, v124
	v_rcp_f32_e32 v126, v126
	v_mul_f32_e32 v121, v121, v125
	v_rcp_f32_e32 v127, v127
	v_mul_f32_e32 v122, v122, v126
	v_rcp_f32_e32 v116, v116
	v_mul_f32_e32 v123, v123, v127
	v_rcp_f32_e32 v117, v117
	v_mul_f32_e32 v112, v112, v116
	v_rcp_f32_e32 v118, v118
	v_mul_f32_e32 v113, v113, v117
	v_rcp_f32_e32 v119, v119
	v_mul_f32_e32 v114, v114, v118
	v_mul_f32_e32 v115, v115, v119
	v_cvt_pk_bf16_f32 v124, v120, v121
	v_cvt_pk_bf16_f32 v125, v122, v123
	v_cvt_pk_bf16_f32 v126, v112, v113
	v_cvt_pk_bf16_f32 v127, v114, v115
	s_movk_i32 s1, 0xb00
	v_lshl_or_b32 v139, s8, 7, v144
	s_mov_b64 s[58:59], -1
	s_andn2_b64 vcc, exec, s[28:29]
	v_mul_lo_u32 v113, v138, s1
	v_add_lshl_u32 v112, v113, v139, 1
	buffer_store_dwordx4 v[124:127], v112, s[36:39], 0 offen sc1
	v_cndmask_b32_e64 v112, 0, 1, s[28:29]
	v_cmp_ne_u32_e64 s[8:9], 1, v112
	v_or_b32_e32 v114, 16, v138
	s_cbranch_vccnz .LBB0_799
	v_ashrrev_i32_e32 v115, 31, v114
	v_lshlrev_b64 v[116:117], 6, v[114:115]
	v_lshl_add_u64 v[146:147], s[94:95], 0, v[116:117]
	global_load_dwordx4 v[116:119], v[146:147], off offset:48
	global_load_dwordx4 v[120:123], v[146:147], off offset:32
	global_load_dwordx4 v[124:127], v[146:147], off offset:16
	s_nop 0
	global_load_dwordx4 v[146:149], v[146:147], off
	s_mov_b64 s[58:59], 0
	s_waitcnt vmcnt(0)
	v_add_f32_e32 v120, v120, v121
	v_add_f32_e32 v122, v122, v123
	v_mov_b32_e32 v150, v147
	v_mov_b32_e32 v151, v148
	v_mov_b32_e32 v147, v149
	v_mov_b32_e32 v148, v125
	v_mov_b32_e32 v149, v126
	v_mov_b32_e32 v125, v127
	v_pk_add_f32 v[146:147], v[150:151], v[146:147]
	v_pk_add_f32 v[124:125], v[148:149], v[124:125]
	v_pk_add_f32 v[146:147], v[146:147], v[146:147] op_sel:[0,1] op_sel_hi:[1,0]
	v_pk_add_f32 v[124:125], v[124:125], v[124:125] op_sel:[0,1] op_sel_hi:[1,0]
	v_mov_b32_e32 v147, v116
	v_mov_b32_e32 v125, v117
	v_mov_b32_e32 v121, v118
	v_mov_b32_e32 v123, v119
	v_pk_add_f32 v[116:117], v[146:147], v[124:125]
	v_pk_add_f32 v[118:119], v[120:121], v[122:123]
	s_nop 0
	v_pk_add_f32 v[116:117], v[116:117], v[118:119]
	s_nop 0
	v_add_f32_e32 v112, v116, v117
	v_fmamk_f32 v112, v112, 0x3a800000, v193
	v_cmp_gt_f32_e32 vcc, s40, v112
	v_mul_f32_e32 v115, 0x4b800000, v112
	s_nop 0
	v_cndmask_b32_e32 v112, v112, v115, vcc
	v_rsq_f32_e32 v112, v112
	s_nop 0
	v_mul_f32_e32 v115, 0x45800000, v112
	v_cndmask_b32_e32 v112, v112, v115, vcc

.LBB0_801:
	s_waitcnt lgkmcnt(0)
	v_mul_f32_e32 v246, 0xbfb8aa3b, v112
	v_mul_f32_e32 v247, v112, v112
	v_rcp_f32_e32 v247, v247
	v_mul_f32_e32 v222, v246, v108
	v_mul_f32_e32 v223, v246, v109
	v_mul_f32_e32 v224, v246, v110
	v_mul_f32_e32 v225, v246, v111
	v_mul_f32_e32 v226, v246, v100
	v_mul_f32_e32 v227, v246, v101
	v_mul_f32_e32 v228, v246, v102
	v_mul_f32_e32 v229, v246, v103
	v_exp_f32_e32 v222, v222
	v_mul_f32_e32 v104, v104, v108
	v_exp_f32_e32 v223, v223
	v_mul_f32_e32 v105, v105, v109
	v_exp_f32_e32 v224, v224
	v_mul_f32_e32 v106, v106, v110
	v_exp_f32_e32 v225, v225
	v_mul_f32_e32 v107, v107, v111
	v_exp_f32_e32 v226, v226
	v_mul_f32_e32 v96, v96, v100
	v_exp_f32_e32 v227, v227
	v_mul_f32_e32 v97, v97, v101
	v_exp_f32_e32 v228, v228
	v_mul_f32_e32 v98, v98, v102
	v_exp_f32_e32 v229, v229
	v_mul_f32_e32 v99, v99, v103
	v_fma_f32 v108, v222, v247, v247
	v_fma_f32 v109, v223, v247, v247
	v_fma_f32 v110, v224, v247, v247
	v_fma_f32 v111, v225, v247, v247
	v_fma_f32 v100, v226, v247, v247
	v_fma_f32 v101, v227, v247, v247
	v_fma_f32 v102, v228, v247, v247
	v_fma_f32 v103, v229, v247, v247
	v_rcp_f32_e32 v108, v108
	v_rcp_f32_e32 v109, v109
	v_mul_f32_e32 v104, v104, v108
	v_rcp_f32_e32 v110, v110
	v_mul_f32_e32 v105, v105, v109
	v_rcp_f32_e32 v111, v111
	v_mul_f32_e32 v106, v106, v110
	v_rcp_f32_e32 v100, v100
	v_mul_f32_e32 v107, v107, v111
	v_rcp_f32_e32 v101, v101
	v_mul_f32_e32 v96, v96, v100
	v_rcp_f32_e32 v102, v102
	v_mul_f32_e32 v97, v97, v101
	v_rcp_f32_e32 v103, v103
	v_mul_f32_e32 v98, v98, v102
	v_mul_f32_e32 v99, v99, v103
	v_cvt_pk_bf16_f32 v108, v104, v105
	v_cvt_pk_bf16_f32 v109, v106, v107
	v_cvt_pk_bf16_f32 v110, v96, v97
	v_cvt_pk_bf16_f32 v111, v98, v99
	s_mov_b64 s[28:29], -1
	s_and_b64 vcc, exec, s[8:9]
	v_add_u32_e32 v97, 0xb000, v113
	v_add_lshl_u32 v96, v97, v139, 1
	buffer_store_dwordx4 v[108:111], v96, s[36:39], 0 offen sc1
	s_nop 1
	v_or_b32_e32 v98, 32, v138
	s_cbranch_vccnz .LBB0_803
	v_ashrrev_i32_e32 v99, 31, v98
	v_lshlrev_b64 v[100:101], 6, v[98:99]
	v_lshl_add_u64 v[112:113], s[94:95], 0, v[100:101]
	global_load_dwordx4 v[100:103], v[112:113], off offset:48
	global_load_dwordx4 v[104:107], v[112:113], off offset:32
	global_load_dwordx4 v[108:111], v[112:113], off offset:16
	s_nop 0
	global_load_dwordx4 v[112:115], v[112:113], off
	s_mov_b64 s[28:29], 0
	s_waitcnt vmcnt(0)
	v_add_f32_e32 v104, v104, v105
	v_add_f32_e32 v106, v106, v107
	v_mov_b32_e32 v116, v113
	v_mov_b32_e32 v117, v114
	v_mov_b32_e32 v113, v115
	v_mov_b32_e32 v114, v109
	v_mov_b32_e32 v115, v110
	v_mov_b32_e32 v109, v111
	v_pk_add_f32 v[112:113], v[116:117], v[112:113]
	v_pk_add_f32 v[108:109], v[114:115], v[108:109]
	v_pk_add_f32 v[112:113], v[112:113], v[112:113] op_sel:[0,1] op_sel_hi:[1,0]
	v_pk_add_f32 v[108:109], v[108:109], v[108:109] op_sel:[0,1] op_sel_hi:[1,0]
	v_mov_b32_e32 v113, v100
	v_mov_b32_e32 v109, v101
	v_mov_b32_e32 v105, v102
	v_mov_b32_e32 v107, v103
	v_pk_add_f32 v[100:101], v[112:113], v[108:109]
	v_pk_add_f32 v[102:103], v[104:105], v[106:107]
	s_nop 0
	v_pk_add_f32 v[100:101], v[100:101], v[102:103]
	s_nop 0
	v_add_f32_e32 v96, v100, v101
	v_fmamk_f32 v96, v96, 0x3a800000, v193
	v_cmp_gt_f32_e32 vcc, s40, v96
	v_mul_f32_e32 v99, 0x4b800000, v96
	s_nop 0
	v_cndmask_b32_e32 v96, v96, v99, vcc
	v_rsq_f32_e32 v96, v96
	s_nop 0
	v_mul_f32_e32 v99, 0x45800000, v96
	v_cndmask_b32_e32 v96, v96, v99, vcc

.LBB0_805:
	s_waitcnt lgkmcnt(0)
	v_mul_f32_e32 v246, 0xbfb8aa3b, v96
	v_mul_f32_e32 v247, v96, v96
	v_rcp_f32_e32 v247, v247
	v_mul_f32_e32 v222, v246, v92
	v_mul_f32_e32 v223, v246, v93
	v_mul_f32_e32 v224, v246, v94
	v_mul_f32_e32 v225, v246, v95
	v_mul_f32_e32 v226, v246, v84
	v_mul_f32_e32 v227, v246, v85
	v_mul_f32_e32 v228, v246, v86
	v_mul_f32_e32 v229, v246, v87
	v_exp_f32_e32 v222, v222
	v_mul_f32_e32 v88, v88, v92
	v_exp_f32_e32 v223, v223
	v_mul_f32_e32 v89, v89, v93
	v_exp_f32_e32 v224, v224
	v_mul_f32_e32 v90, v90, v94
	v_exp_f32_e32 v225, v225
	v_mul_f32_e32 v91, v91, v95
	v_exp_f32_e32 v226, v226
	v_mul_f32_e32 v80, v80, v84
	v_exp_f32_e32 v227, v227
	v_mul_f32_e32 v81, v81, v85
	v_exp_f32_e32 v228, v228
	v_mul_f32_e32 v82, v82, v86
	v_exp_f32_e32 v229, v229
	v_mul_f32_e32 v83, v83, v87
	v_fma_f32 v92, v222, v247, v247
	v_fma_f32 v93, v223, v247, v247
	v_fma_f32 v94, v224, v247, v247
	v_fma_f32 v95, v225, v247, v247
	v_fma_f32 v84, v226, v247, v247
	v_fma_f32 v85, v227, v247, v247
	v_fma_f32 v86, v228, v247, v247
	v_fma_f32 v87, v229, v247, v247
	v_rcp_f32_e32 v92, v92
	v_rcp_f32_e32 v93, v93
	v_mul_f32_e32 v88, v88, v92
	v_rcp_f32_e32 v94, v94
	v_mul_f32_e32 v89, v89, v93
	v_rcp_f32_e32 v95, v95
	v_mul_f32_e32 v90, v90, v94
	v_rcp_f32_e32 v84, v84
	v_mul_f32_e32 v91, v91, v95
	v_rcp_f32_e32 v85, v85
	v_mul_f32_e32 v80, v80, v84
	v_rcp_f32_e32 v86, v86
	v_mul_f32_e32 v81, v81, v85
	v_rcp_f32_e32 v87, v87
	v_mul_f32_e32 v82, v82, v86
	v_mul_f32_e32 v83, v83, v87
	v_cvt_pk_bf16_f32 v92, v88, v89
	v_cvt_pk_bf16_f32 v93, v90, v91
	v_cvt_pk_bf16_f32 v94, v80, v81
	v_cvt_pk_bf16_f32 v95, v82, v83
	s_mov_b64 s[28:29], -1
	s_and_b64 vcc, exec, s[8:9]
	v_add_u32_e32 v81, 0xb000, v97
	v_add_lshl_u32 v80, v81, v139, 1
	buffer_store_dwordx4 v[92:95], v80, s[36:39], 0 offen sc1
	s_nop 1
	v_or_b32_e32 v82, 48, v138
	s_cbranch_vccnz .LBB0_807
	v_ashrrev_i32_e32 v83, 31, v82
	v_lshlrev_b64 v[84:85], 6, v[82:83]
	v_lshl_add_u64 v[96:97], s[94:95], 0, v[84:85]
	global_load_dwordx4 v[84:87], v[96:97], off offset:48
	global_load_dwordx4 v[88:91], v[96:97], off offset:32
	global_load_dwordx4 v[92:95], v[96:97], off offset:16
	s_nop 0
	global_load_dwordx4 v[96:99], v[96:97], off
	s_mov_b64 s[28:29], 0
	s_waitcnt vmcnt(0)
	v_add_f32_e32 v88, v88, v89
	v_add_f32_e32 v90, v90, v91
	v_mov_b32_e32 v100, v97
	v_mov_b32_e32 v101, v98
	v_mov_b32_e32 v97, v99
	v_mov_b32_e32 v98, v93
	v_mov_b32_e32 v99, v94
	v_mov_b32_e32 v93, v95
	v_pk_add_f32 v[96:97], v[100:101], v[96:97]
	v_pk_add_f32 v[92:93], v[98:99], v[92:93]
	v_pk_add_f32 v[96:97], v[96:97], v[96:97] op_sel:[0,1] op_sel_hi:[1,0]
	v_pk_add_f32 v[92:93], v[92:93], v[92:93] op_sel:[0,1] op_sel_hi:[1,0]
	v_mov_b32_e32 v97, v84
	v_mov_b32_e32 v93, v85
	v_mov_b32_e32 v89, v86
	v_mov_b32_e32 v91, v87
	v_pk_add_f32 v[84:85], v[96:97], v[92:93]
	v_pk_add_f32 v[86:87], v[88:89], v[90:91]
	s_nop 0
	v_pk_add_f32 v[84:85], v[84:85], v[86:87]
	s_nop 0
	v_add_f32_e32 v80, v84, v85
	v_fmamk_f32 v80, v80, 0x3a800000, v193
	v_cmp_gt_f32_e32 vcc, s40, v80
	v_mul_f32_e32 v83, 0x4b800000, v80
	s_nop 0
	v_cndmask_b32_e32 v80, v80, v83, vcc
	v_rsq_f32_e32 v80, v80
	s_nop 0
	v_mul_f32_e32 v83, 0x45800000, v80
	v_cndmask_b32_e32 v80, v80, v83, vcc

.LBB0_809:
	s_waitcnt lgkmcnt(0)
	v_mul_f32_e32 v246, 0xbfb8aa3b, v80
	v_mul_f32_e32 v247, v80, v80
	v_rcp_f32_e32 v247, v247
	v_mul_f32_e32 v222, v246, v76
	v_mul_f32_e32 v223, v246, v77
	v_mul_f32_e32 v224, v246, v78
	v_mul_f32_e32 v225, v246, v79
	v_mul_f32_e32 v226, v246, v68
	v_mul_f32_e32 v227, v246, v69
	v_mul_f32_e32 v228, v246, v70
	v_mul_f32_e32 v229, v246, v71
	v_exp_f32_e32 v222, v222
	v_mul_f32_e32 v72, v72, v76
	v_exp_f32_e32 v223, v223
	v_mul_f32_e32 v73, v73, v77
	v_exp_f32_e32 v224, v224
	v_mul_f32_e32 v74, v74, v78
	v_exp_f32_e32 v225, v225
	v_mul_f32_e32 v75, v75, v79
	v_exp_f32_e32 v226, v226
	v_mul_f32_e32 v64, v64, v68
	v_exp_f32_e32 v227, v227
	v_mul_f32_e32 v65, v65, v69
	v_exp_f32_e32 v228, v228
	v_mul_f32_e32 v66, v66, v70
	v_exp_f32_e32 v229, v229
	v_mul_f32_e32 v67, v67, v71
	v_fma_f32 v76, v222, v247, v247
	v_fma_f32 v77, v223, v247, v247
	v_fma_f32 v78, v224, v247, v247
	v_fma_f32 v79, v225, v247, v247
	v_fma_f32 v68, v226, v247, v247
	v_fma_f32 v69, v227, v247, v247
	v_fma_f32 v70, v228, v247, v247
	v_fma_f32 v71, v229, v247, v247
	v_rcp_f32_e32 v76, v76
	v_rcp_f32_e32 v77, v77
	v_mul_f32_e32 v72, v72, v76
	v_rcp_f32_e32 v78, v78
	v_mul_f32_e32 v73, v73, v77
	v_rcp_f32_e32 v79, v79
	v_mul_f32_e32 v74, v74, v78
	v_rcp_f32_e32 v68, v68
	v_mul_f32_e32 v75, v75, v79
	v_rcp_f32_e32 v69, v69
	v_mul_f32_e32 v64, v64, v68
	v_rcp_f32_e32 v70, v70
	v_mul_f32_e32 v65, v65, v69
	v_rcp_f32_e32 v71, v71
	v_mul_f32_e32 v66, v66, v70
	v_mul_f32_e32 v67, v67, v71
	v_cvt_pk_bf16_f32 v76, v72, v73
	v_cvt_pk_bf16_f32 v77, v74, v75
	v_cvt_pk_bf16_f32 v78, v64, v65
	v_cvt_pk_bf16_f32 v79, v66, v67
	s_mov_b64 s[28:29], -1
	s_and_b64 vcc, exec, s[8:9]
	v_add_u32_e32 v65, 0xb000, v81
	v_add_lshl_u32 v64, v65, v139, 1
	buffer_store_dwordx4 v[76:79], v64, s[36:39], 0 offen sc1
	s_nop 1
	v_add_u32_e32 v66, 0x80, v138
	s_cbranch_vccnz .LBB0_811
	v_ashrrev_i32_e32 v67, 31, v66
	v_lshlrev_b64 v[68:69], 6, v[66:67]
	v_lshl_add_u64 v[80:81], s[94:95], 0, v[68:69]
	global_load_dwordx4 v[68:71], v[80:81], off offset:48
	global_load_dwordx4 v[72:75], v[80:81], off offset:32
	global_load_dwordx4 v[76:79], v[80:81], off offset:16
	s_nop 0
	global_load_dwordx4 v[80:83], v[80:81], off
	s_mov_b64 s[28:29], 0
	s_waitcnt vmcnt(0)
	v_add_f32_e32 v72, v72, v73
	v_add_f32_e32 v74, v74, v75
	v_mov_b32_e32 v84, v81
	v_mov_b32_e32 v85, v82
	v_mov_b32_e32 v81, v83
	v_mov_b32_e32 v82, v77
	v_mov_b32_e32 v83, v78
	v_mov_b32_e32 v77, v79
	v_pk_add_f32 v[80:81], v[84:85], v[80:81]
	v_pk_add_f32 v[76:77], v[82:83], v[76:77]
	v_pk_add_f32 v[80:81], v[80:81], v[80:81] op_sel:[0,1] op_sel_hi:[1,0]
	v_pk_add_f32 v[76:77], v[76:77], v[76:77] op_sel:[0,1] op_sel_hi:[1,0]
	v_mov_b32_e32 v81, v68
	v_mov_b32_e32 v77, v69
	v_mov_b32_e32 v73, v70
	v_mov_b32_e32 v75, v71
	v_pk_add_f32 v[68:69], v[80:81], v[76:77]
	v_pk_add_f32 v[70:71], v[72:73], v[74:75]
	s_nop 0
	v_pk_add_f32 v[68:69], v[68:69], v[70:71]
	s_nop 0
	v_add_f32_e32 v64, v68, v69
	v_fmamk_f32 v64, v64, 0x3a800000, v193
	v_cmp_gt_f32_e32 vcc, s40, v64
	v_mul_f32_e32 v67, 0x4b800000, v64
	s_nop 0
	v_cndmask_b32_e32 v64, v64, v67, vcc
	v_rsq_f32_e32 v64, v64
	s_nop 0
	v_mul_f32_e32 v67, 0x45800000, v64
	v_cndmask_b32_e32 v64, v64, v67, vcc

.LBB0_813:
	s_waitcnt lgkmcnt(0)
	v_mul_f32_e32 v246, 0xbfb8aa3b, v64
	v_mul_f32_e32 v247, v64, v64
	v_rcp_f32_e32 v247, v247
	v_mul_f32_e32 v222, v246, v60
	v_mul_f32_e32 v223, v246, v61
	v_mul_f32_e32 v224, v246, v62
	v_mul_f32_e32 v225, v246, v63
	v_mul_f32_e32 v226, v246, v52
	v_mul_f32_e32 v227, v246, v53
	v_mul_f32_e32 v228, v246, v54
	v_mul_f32_e32 v229, v246, v55
	v_exp_f32_e32 v222, v222
	v_mul_f32_e32 v56, v56, v60
	v_exp_f32_e32 v223, v223
	v_mul_f32_e32 v57, v57, v61
	v_exp_f32_e32 v224, v224
	v_mul_f32_e32 v58, v58, v62
	v_exp_f32_e32 v225, v225
	v_mul_f32_e32 v59, v59, v63
	v_exp_f32_e32 v226, v226
	v_mul_f32_e32 v48, v48, v52
	v_exp_f32_e32 v227, v227
	v_mul_f32_e32 v49, v49, v53
	v_exp_f32_e32 v228, v228
	v_mul_f32_e32 v50, v50, v54
	v_exp_f32_e32 v229, v229
	v_mul_f32_e32 v51, v51, v55
	v_fma_f32 v60, v222, v247, v247
	v_fma_f32 v61, v223, v247, v247
	v_fma_f32 v62, v224, v247, v247
	v_fma_f32 v63, v225, v247, v247
	v_fma_f32 v52, v226, v247, v247
	v_fma_f32 v53, v227, v247, v247
	v_fma_f32 v54, v228, v247, v247
	v_fma_f32 v55, v229, v247, v247
	v_rcp_f32_e32 v60, v60
	v_rcp_f32_e32 v61, v61
	v_mul_f32_e32 v56, v56, v60
	v_rcp_f32_e32 v62, v62
	v_mul_f32_e32 v57, v57, v61
	v_rcp_f32_e32 v63, v63
	v_mul_f32_e32 v58, v58, v62
	v_rcp_f32_e32 v52, v52
	v_mul_f32_e32 v59, v59, v63
	v_rcp_f32_e32 v53, v53
	v_mul_f32_e32 v48, v48, v52
	v_rcp_f32_e32 v54, v54
	v_mul_f32_e32 v49, v49, v53
	v_rcp_f32_e32 v55, v55
	v_mul_f32_e32 v50, v50, v54
	v_mul_f32_e32 v51, v51, v55
	v_cvt_pk_bf16_f32 v60, v56, v57
	v_cvt_pk_bf16_f32 v61, v58, v59
	v_cvt_pk_bf16_f32 v62, v48, v49
	v_cvt_pk_bf16_f32 v63, v50, v51
	s_mov_b64 s[28:29], -1
	s_and_b64 vcc, exec, s[8:9]
	v_add_u32_e32 v49, 0x37000, v65
	v_add_lshl_u32 v48, v49, v139, 1
	buffer_store_dwordx4 v[60:63], v48, s[36:39], 0 offen sc1
	s_nop 1
	v_add_u32_e32 v50, 0x90, v138
	s_cbranch_vccnz .LBB0_815
	v_ashrrev_i32_e32 v51, 31, v50
	v_lshlrev_b64 v[52:53], 6, v[50:51]
	v_lshl_add_u64 v[64:65], s[94:95], 0, v[52:53]
	global_load_dwordx4 v[52:55], v[64:65], off offset:48
	global_load_dwordx4 v[56:59], v[64:65], off offset:32
	global_load_dwordx4 v[60:63], v[64:65], off offset:16
	s_nop 0
	global_load_dwordx4 v[64:67], v[64:65], off
	s_mov_b64 s[28:29], 0
	s_waitcnt vmcnt(0)
	v_add_f32_e32 v56, v56, v57
	v_add_f32_e32 v58, v58, v59
	v_mov_b32_e32 v68, v65
	v_mov_b32_e32 v69, v66
	v_mov_b32_e32 v65, v67
	v_mov_b32_e32 v66, v61
	v_mov_b32_e32 v67, v62
	v_mov_b32_e32 v61, v63
	v_pk_add_f32 v[64:65], v[68:69], v[64:65]
	v_pk_add_f32 v[60:61], v[66:67], v[60:61]
	v_pk_add_f32 v[64:65], v[64:65], v[64:65] op_sel:[0,1] op_sel_hi:[1,0]
	v_pk_add_f32 v[60:61], v[60:61], v[60:61] op_sel:[0,1] op_sel_hi:[1,0]
	v_mov_b32_e32 v65, v52
	v_mov_b32_e32 v61, v53
	v_mov_b32_e32 v57, v54
	v_mov_b32_e32 v59, v55
	v_pk_add_f32 v[52:53], v[64:65], v[60:61]
	v_pk_add_f32 v[54:55], v[56:57], v[58:59]
	s_nop 0
	v_pk_add_f32 v[52:53], v[52:53], v[54:55]
	s_nop 0
	v_add_f32_e32 v48, v52, v53
	v_fmamk_f32 v48, v48, 0x3a800000, v193
	v_cmp_gt_f32_e32 vcc, s40, v48
	v_mul_f32_e32 v51, 0x4b800000, v48
	s_nop 0
	v_cndmask_b32_e32 v48, v48, v51, vcc
	v_rsq_f32_e32 v48, v48
	s_nop 0
	v_mul_f32_e32 v51, 0x45800000, v48
	v_cndmask_b32_e32 v48, v48, v51, vcc

.LBB0_817:
	s_waitcnt lgkmcnt(0)
	v_mul_f32_e32 v246, 0xbfb8aa3b, v48
	v_mul_f32_e32 v247, v48, v48
	v_rcp_f32_e32 v247, v247
	v_mul_f32_e32 v222, v246, v44
	v_mul_f32_e32 v223, v246, v45
	v_mul_f32_e32 v224, v246, v46
	v_mul_f32_e32 v225, v246, v47
	v_mul_f32_e32 v226, v246, v36
	v_mul_f32_e32 v227, v246, v37
	v_mul_f32_e32 v228, v246, v38
	v_mul_f32_e32 v229, v246, v39
	v_exp_f32_e32 v222, v222
	v_mul_f32_e32 v40, v40, v44
	v_exp_f32_e32 v223, v223
	v_mul_f32_e32 v41, v41, v45
	v_exp_f32_e32 v224, v224
	v_mul_f32_e32 v42, v42, v46
	v_exp_f32_e32 v225, v225
	v_mul_f32_e32 v43, v43, v47
	v_exp_f32_e32 v226, v226
	v_mul_f32_e32 v32, v32, v36
	v_exp_f32_e32 v227, v227
	v_mul_f32_e32 v33, v33, v37
	v_exp_f32_e32 v228, v228
	v_mul_f32_e32 v34, v34, v38
	v_exp_f32_e32 v229, v229
	v_mul_f32_e32 v35, v35, v39
	v_fma_f32 v44, v222, v247, v247
	v_fma_f32 v45, v223, v247, v247
	v_fma_f32 v46, v224, v247, v247
	v_fma_f32 v47, v225, v247, v247
	v_fma_f32 v36, v226, v247, v247
	v_fma_f32 v37, v227, v247, v247
	v_fma_f32 v38, v228, v247, v247
	v_fma_f32 v39, v229, v247, v247
	v_rcp_f32_e32 v44, v44
	v_rcp_f32_e32 v45, v45
	v_mul_f32_e32 v40, v40, v44
	v_rcp_f32_e32 v46, v46
	v_mul_f32_e32 v41, v41, v45
	v_rcp_f32_e32 v47, v47
	v_mul_f32_e32 v42, v42, v46
	v_rcp_f32_e32 v36, v36
	v_mul_f32_e32 v43, v43, v47
	v_rcp_f32_e32 v37, v37
	v_mul_f32_e32 v32, v32, v36
	v_rcp_f32_e32 v38, v38
	v_mul_f32_e32 v33, v33, v37
	v_rcp_f32_e32 v39, v39
	v_mul_f32_e32 v34, v34, v38
	v_mul_f32_e32 v35, v35, v39
	v_cvt_pk_bf16_f32 v44, v40, v41
	v_cvt_pk_bf16_f32 v45, v42, v43
	v_cvt_pk_bf16_f32 v46, v32, v33
	v_cvt_pk_bf16_f32 v47, v34, v35
	s_mov_b64 s[28:29], -1
	s_and_b64 vcc, exec, s[8:9]
	v_add_u32_e32 v35, 0xb000, v49
	v_add_lshl_u32 v32, v35, v139, 1
	buffer_store_dwordx4 v[44:47], v32, s[36:39], 0 offen sc1
	v_add_u32_e32 v32, 0xa0, v138
	s_cbranch_vccnz .LBB0_819
	v_ashrrev_i32_e32 v33, 31, v32
	v_lshlrev_b64 v[36:37], 6, v[32:33]
	v_lshl_add_u64 v[48:49], s[94:95], 0, v[36:37]
	global_load_dwordx4 v[36:39], v[48:49], off offset:48
	global_load_dwordx4 v[40:43], v[48:49], off offset:32
	global_load_dwordx4 v[44:47], v[48:49], off offset:16
	s_nop 0
	global_load_dwordx4 v[48:51], v[48:49], off
	s_mov_b64 s[28:29], 0
	s_waitcnt vmcnt(0)
	v_add_f32_e32 v40, v40, v41
	v_add_f32_e32 v42, v42, v43
	v_mov_b32_e32 v52, v49
	v_mov_b32_e32 v53, v50
	v_mov_b32_e32 v49, v51
	v_mov_b32_e32 v50, v45
	v_mov_b32_e32 v51, v46
	v_mov_b32_e32 v45, v47
	v_pk_add_f32 v[48:49], v[52:53], v[48:49]
	v_pk_add_f32 v[44:45], v[50:51], v[44:45]
	v_pk_add_f32 v[48:49], v[48:49], v[48:49] op_sel:[0,1] op_sel_hi:[1,0]
	v_pk_add_f32 v[44:45], v[44:45], v[44:45] op_sel:[0,1] op_sel_hi:[1,0]
	v_mov_b32_e32 v49, v36
	v_mov_b32_e32 v45, v37
	v_mov_b32_e32 v41, v38
	v_mov_b32_e32 v43, v39
	v_pk_add_f32 v[36:37], v[48:49], v[44:45]
	v_pk_add_f32 v[38:39], v[40:41], v[42:43]
	s_nop 0
	v_pk_add_f32 v[36:37], v[36:37], v[38:39]
	s_nop 0
	v_add_f32_e32 v33, v36, v37
	v_fmamk_f32 v33, v33, 0x3a800000, v193
	v_cmp_gt_f32_e32 vcc, s40, v33
	v_mul_f32_e32 v34, 0x4b800000, v33
	s_nop 0
	v_cndmask_b32_e32 v33, v33, v34, vcc
	v_rsq_f32_e32 v33, v33
	s_nop 0
	v_mul_f32_e32 v34, 0x45800000, v33
	v_cndmask_b32_e32 v34, v33, v34, vcc

.LBB0_821:
	s_waitcnt lgkmcnt(0)
	v_mul_f32_e32 v246, 0xbfb8aa3b, v34
	v_mul_f32_e32 v247, v34, v34
	v_rcp_f32_e32 v247, v247
	v_mul_f32_e32 v222, v246, v28
	v_mul_f32_e32 v223, v246, v29
	v_mul_f32_e32 v224, v246, v30
	v_mul_f32_e32 v225, v246, v31
	v_mul_f32_e32 v226, v246, v20
	v_mul_f32_e32 v227, v246, v21
	v_mul_f32_e32 v228, v246, v22
	v_mul_f32_e32 v229, v246, v23
	v_exp_f32_e32 v222, v222
	v_mul_f32_e32 v24, v24, v28
	v_exp_f32_e32 v223, v223
	v_mul_f32_e32 v25, v25, v29
	v_exp_f32_e32 v224, v224
	v_mul_f32_e32 v26, v26, v30
	v_exp_f32_e32 v225, v225
	v_mul_f32_e32 v27, v27, v31
	v_exp_f32_e32 v226, v226
	v_mul_f32_e32 v16, v16, v20
	v_exp_f32_e32 v227, v227
	v_mul_f32_e32 v17, v17, v21
	v_exp_f32_e32 v228, v228
	v_mul_f32_e32 v18, v18, v22
	v_exp_f32_e32 v229, v229
	v_mul_f32_e32 v19, v19, v23
	v_fma_f32 v28, v222, v247, v247
	v_fma_f32 v29, v223, v247, v247
	v_fma_f32 v30, v224, v247, v247
	v_fma_f32 v31, v225, v247, v247
	v_fma_f32 v20, v226, v247, v247
	v_fma_f32 v21, v227, v247, v247
	v_fma_f32 v22, v228, v247, v247
	v_fma_f32 v23, v229, v247, v247
	v_rcp_f32_e32 v28, v28
	v_rcp_f32_e32 v29, v29
	v_mul_f32_e32 v24, v24, v28
	v_rcp_f32_e32 v30, v30
	v_mul_f32_e32 v25, v25, v29
	v_rcp_f32_e32 v31, v31
	v_mul_f32_e32 v26, v26, v30
	v_rcp_f32_e32 v20, v20
	v_mul_f32_e32 v27, v27, v31
	v_rcp_f32_e32 v21, v21
	v_mul_f32_e32 v16, v16, v20
	v_rcp_f32_e32 v22, v22
	v_mul_f32_e32 v17, v17, v21
	v_rcp_f32_e32 v23, v23
	v_mul_f32_e32 v18, v18, v22
	v_mul_f32_e32 v19, v19, v23
	v_cvt_pk_bf16_f32 v28, v24, v25
	v_cvt_pk_bf16_f32 v29, v26, v27
	v_cvt_pk_bf16_f32 v30, v16, v17
	v_cvt_pk_bf16_f32 v31, v18, v19
	s_and_b64 vcc, exec, s[8:9]
	s_mov_b64 s[8:9], -1
	v_add_u32_e32 v17, 0xb000, v35
	v_add_lshl_u32 v16, v17, v139, 1
	buffer_store_dwordx4 v[28:31], v16, s[36:39], 0 offen sc1
	s_nop 1
	v_add_u32_e32 v18, 0xb0, v138
	s_cbranch_vccnz .LBB0_823
	v_ashrrev_i32_e32 v19, 31, v18
	v_lshlrev_b64 v[20:21], 6, v[18:19]
	v_lshl_add_u64 v[32:33], s[94:95], 0, v[20:21]
	global_load_dwordx4 v[20:23], v[32:33], off offset:48
	global_load_dwordx4 v[24:27], v[32:33], off offset:32
	global_load_dwordx4 v[28:31], v[32:33], off offset:16
	s_nop 0
	global_load_dwordx4 v[32:35], v[32:33], off
	s_mov_b64 s[8:9], 0
	s_waitcnt vmcnt(0)
	v_add_f32_e32 v24, v24, v25
	v_add_f32_e32 v26, v26, v27
	v_mov_b32_e32 v36, v33
	v_mov_b32_e32 v37, v34
	v_mov_b32_e32 v33, v35
	v_mov_b32_e32 v34, v29
	v_mov_b32_e32 v35, v30
	v_mov_b32_e32 v29, v31
	v_pk_add_f32 v[32:33], v[36:37], v[32:33]
	v_pk_add_f32 v[28:29], v[34:35], v[28:29]
	v_pk_add_f32 v[32:33], v[32:33], v[32:33] op_sel:[0,1] op_sel_hi:[1,0]
	v_pk_add_f32 v[28:29], v[28:29], v[28:29] op_sel:[0,1] op_sel_hi:[1,0]
	v_mov_b32_e32 v33, v20
	v_mov_b32_e32 v29, v21
	v_mov_b32_e32 v25, v22
	v_mov_b32_e32 v27, v23
	v_pk_add_f32 v[20:21], v[32:33], v[28:29]
	v_pk_add_f32 v[22:23], v[24:25], v[26:27]
	s_nop 0
	v_pk_add_f32 v[20:21], v[20:21], v[22:23]
	s_nop 0
	v_add_f32_e32 v16, v20, v21
	v_fmamk_f32 v16, v16, 0x3a800000, v193
	v_cmp_gt_f32_e32 vcc, s40, v16
	v_mul_f32_e32 v19, 0x4b800000, v16
	s_nop 0
	v_cndmask_b32_e32 v16, v16, v19, vcc
	v_rsq_f32_e32 v16, v16
	s_nop 0
	v_mul_f32_e32 v19, 0x45800000, v16
	v_cndmask_b32_e32 v16, v16, v19, vcc
